# v29 + GLA scan state stores (bf16 ST, 512 B contiguous per instruction) issued write-through
# speedup vs baseline: 1.0106x; 1.0052x over previous
; __device__ __forceinline__ unsigned pk2(float lo, float hi) { return f2bf(lo) | (f2bf(hi) << 16); }
; __device__ __forceinline__ void gla_scan(const float* UPD, const float* DEC, bf16* ST, int gtid, int gthreads) {
;     ...
;         for (int c0 = 0; c0 < 64; c0 += 16) {
;             f32x4 dv[16], uv[16];
; #pragma unroll
;             for (int i = 0; i < 16; ++i) { const size_t unit = (size_t)((c0 + i) * 4 + h); dv[i] = *(const f32x4*)(DEC + unit * 64 + 4 * kq); uv[i] = *(const f32x4*)(UPD + unit * 8192 + v * 64 + 4 * kq); }
;             asm volatile("" : "+v"(dv[0]), "+v"(dv[1]), "+v"(dv[2]), "+v"(dv[3]), "+v"(dv[4]), "+v"(dv[5]), "+v"(dv[6]), "+v"(dv[7]) :: "memory");
;             asm volatile("" : "+v"(dv[8]), "+v"(dv[9]), "+v"(dv[10]), "+v"(dv[11]), "+v"(dv[12]), "+v"(dv[13]), "+v"(dv[14]), "+v"(dv[15]) :: "memory");
;             asm volatile("" : "+v"(uv[0]), "+v"(uv[1]), "+v"(uv[2]), "+v"(uv[3]), "+v"(uv[4]), "+v"(uv[5]), "+v"(uv[6]), "+v"(uv[7]) :: "memory");
;             asm volatile("" : "+v"(uv[8]), "+v"(uv[9]), "+v"(uv[10]), "+v"(uv[11]), "+v"(uv[12]), "+v"(uv[13]), "+v"(uv[14]), "+v"(uv[15]) :: "memory");
; #pragma unroll
;             for (int i = 0; i < 16; ++i) {
;                 const size_t unit = (size_t)((c0 + i) * 4 + h);
;                 s = dv[i] * s + uv[i];
;                 u32x2 w; w.x = pk2(s[0], s[1]); w.y = pk2(s[2], s[3]);
;                 *(u32x2*)(ST + unit * 8192 + v * 64 + 4 * kq) = w;
;             }
.LBB0_473:
	v_lshl_add_u64 v[26:27], s[34:35], 0, v[18:19]
	v_add_co_u32_e32 v0, vcc, 0x401000, v26
	v_lshl_add_u64 v[24:25], s[34:35], 0, v[16:17]
	s_nop 0
	v_addc_co_u32_e32 v1, vcc, 0, v27, vcc
	v_add_co_u32_e32 v2, vcc, 0x400000, v26
	global_load_dwordx4 v[48:51], v[0:1], off offset:3072
	global_load_dwordx4 v[52:55], v[0:1], off offset:2048
	global_load_dwordx4 v[56:59], v[0:1], off offset:1024
	global_load_dwordx4 v[60:63], v[0:1], off
	v_addc_co_u32_e32 v3, vcc, 0, v27, vcc
	v_add_co_u32_e32 v80, vcc, 0x403000, v26
	global_load_dwordx4 v[64:67], v[2:3], off offset:3072
	global_load_dwordx4 v[68:71], v[2:3], off offset:2048
	global_load_dwordx4 v[72:75], v[2:3], off offset:1024
	global_load_dwordx4 v[76:79], v[2:3], off
	v_addc_co_u32_e32 v81, vcc, 0, v27, vcc
	v_add_co_u32_e32 v26, vcc, 0x402000, v26
	global_load_dwordx4 v[0:3], v[80:81], off offset:3072
	global_load_dwordx4 v[4:7], v[80:81], off offset:2048
	global_load_dwordx4 v[8:11], v[80:81], off offset:1024
	s_nop 0
	global_load_dwordx4 v[80:83], v[80:81], off
	v_addc_co_u32_e32 v27, vcc, 0, v27, vcc
	v_add_co_u32_e32 v100, vcc, 0x190e0000, v24
	global_load_dwordx4 v[84:87], v[26:27], off offset:3072
	global_load_dwordx4 v[88:91], v[26:27], off offset:2048
	global_load_dwordx4 v[92:95], v[26:27], off offset:1024
	global_load_dwordx4 v[96:99], v[26:27], off
	v_addc_co_u32_e32 v101, vcc, 0, v25, vcc
	v_add_co_u32_e32 v26, vcc, 0x190c0000, v24
	v_lshl_add_u64 v[28:29], s[34:35], 0, v[14:15]
	s_nop 0
	v_addc_co_u32_e32 v27, vcc, 0, v25, vcc
	v_add_co_u32_e32 v108, vcc, 0x190a0000, v24
	global_load_dwordx4 v[100:103], v[100:101], off
	s_nop 0
	global_load_dwordx4 v[104:107], v[26:27], off
	v_addc_co_u32_e32 v109, vcc, 0, v25, vcc
	v_add_co_u32_e32 v26, vcc, 0x19080000, v24
	v_add_co_u32_e64 v160, s[0:1], s21, v28
	s_nop 0
	v_addc_co_u32_e32 v27, vcc, 0, v25, vcc
	v_add_co_u32_e32 v116, vcc, 0x19060000, v24
	global_load_dwordx4 v[108:111], v[108:109], off
	s_nop 0
	global_load_dwordx4 v[112:115], v[26:27], off
	v_addc_co_u32_e32 v117, vcc, 0, v25, vcc
	v_add_co_u32_e32 v26, vcc, 0x19040000, v24
	v_addc_co_u32_e64 v161, s[0:1], 0, v29, s[0:1]
	s_nop 0
	v_addc_co_u32_e32 v27, vcc, 0, v25, vcc
	v_add_co_u32_e32 v124, vcc, 0x19020000, v24
	global_load_dwordx4 v[116:119], v[116:117], off
	s_nop 0
	global_load_dwordx4 v[120:123], v[26:27], off
	v_addc_co_u32_e32 v125, vcc, 0, v25, vcc
	v_add_co_u32_e32 v26, vcc, 0x19000000, v24
	v_add_co_u32_e64 v162, s[0:1], s28, v28
	s_nop 0
	v_addc_co_u32_e32 v27, vcc, 0, v25, vcc
	v_add_co_u32_e32 v132, vcc, 0x191e0000, v24
	global_load_dwordx4 v[124:127], v[124:125], off
	s_nop 0
	global_load_dwordx4 v[128:131], v[26:27], off
	v_addc_co_u32_e32 v133, vcc, 0, v25, vcc
	v_add_co_u32_e32 v26, vcc, 0x191c0000, v24
	v_addc_co_u32_e64 v163, s[0:1], 0, v29, s[0:1]
	s_nop 0
	v_addc_co_u32_e32 v27, vcc, 0, v25, vcc
	v_add_co_u32_e32 v140, vcc, 0x191a0000, v24
	global_load_dwordx4 v[132:135], v[132:133], off
	s_nop 0
	global_load_dwordx4 v[136:139], v[26:27], off
	v_addc_co_u32_e32 v141, vcc, 0, v25, vcc
	v_add_co_u32_e32 v26, vcc, 0x19180000, v24
	v_add_co_u32_e64 v164, s[0:1], s29, v28
	s_nop 0
	v_addc_co_u32_e32 v27, vcc, 0, v25, vcc
	v_add_co_u32_e32 v148, vcc, 0x19160000, v24
	global_load_dwordx4 v[140:143], v[140:141], off
	s_nop 0
	global_load_dwordx4 v[144:147], v[26:27], off
	v_addc_co_u32_e32 v149, vcc, 0, v25, vcc
	v_add_co_u32_e32 v26, vcc, 0x19140000, v24
	v_addc_co_u32_e64 v165, s[0:1], 0, v29, s[0:1]
	s_nop 0
	v_addc_co_u32_e32 v27, vcc, 0, v25, vcc
	v_add_co_u32_e32 v156, vcc, 0x19120000, v24
	global_load_dwordx4 v[148:151], v[148:149], off
	s_nop 0
	global_load_dwordx4 v[152:155], v[26:27], off
	v_addc_co_u32_e32 v157, vcc, 0, v25, vcc
	v_add_co_u32_e32 v158, vcc, 0x19100000, v24
	v_add_co_u32_e64 v166, s[0:1], s30, v28
	s_nop 0
	v_addc_co_u32_e32 v159, vcc, 0, v25, vcc
	global_load_dwordx4 v[24:27], v[156:157], off
	s_nop 0
	global_load_dwordx4 v[156:159], v[158:159], off
	v_addc_co_u32_e64 v167, s[0:1], 0, v29, s[0:1]
	v_add_co_u32_e64 v168, s[0:1], s31, v28
	s_waitcnt vmcnt(24)
	s_waitcnt vmcnt(16)
	s_waitcnt vmcnt(8)
	v_addc_co_u32_e64 v169, s[0:1], 0, v29, s[0:1]
	v_add_co_u32_e64 v170, s[0:1], s37, v28
	v_pk_fma_f32 v[22:23], v[22:23], v[78:79], v[130:131]
	s_nop 0
	v_addc_co_u32_e64 v171, s[0:1], 0, v29, s[0:1]
	v_pk_fma_f32 v[20:21], v[20:21], v[76:77], v[128:129]
	v_add_co_u32_e64 v172, s[0:1], s39, v28
	v_bfe_u32 v12, v20, 16, 1
	v_bfe_u32 v76, v21, 16, 1
	v_bfe_u32 v77, v22, 16, 1
	v_bfe_u32 v78, v23, 16, 1
	v_pk_fma_f32 v[74:75], v[74:75], v[22:23], v[126:127]
	v_pk_fma_f32 v[72:73], v[72:73], v[20:21], v[124:125]
	v_addc_co_u32_e64 v173, s[0:1], 0, v29, s[0:1]
	v_add3_u32 v12, v20, v12, s11
	v_add3_u32 v76, v21, v76, s11
	v_add3_u32 v77, v22, v77, s11
	v_add3_u32 v78, v23, v78, s11
	v_bfe_u32 v79, v72, 16, 1
	v_bfe_u32 v124, v73, 16, 1
	v_bfe_u32 v125, v74, 16, 1
	v_bfe_u32 v126, v75, 16, 1
	v_pk_fma_f32 v[20:21], v[70:71], v[74:75], v[122:123]
	v_pk_fma_f32 v[22:23], v[68:69], v[72:73], v[120:121]
	v_add_co_u32_e64 v44, s[0:1], s56, v28
	v_lshrrev_b32_e32 v12, 16, v12
	v_lshrrev_b32_e32 v69, 16, v77
	v_add3_u32 v70, v72, v79, s11
	v_add3_u32 v71, v73, v124, s11
	v_add3_u32 v72, v74, v125, s11
	v_add3_u32 v73, v75, v126, s11
	v_bfe_u32 v74, v22, 16, 1
	v_bfe_u32 v75, v23, 16, 1
	v_bfe_u32 v77, v20, 16, 1
	v_bfe_u32 v79, v21, 16, 1
	v_pk_fma_f32 v[66:67], v[66:67], v[20:21], v[118:119]
	v_pk_fma_f32 v[64:65], v[64:65], v[22:23], v[116:117]
	v_addc_co_u32_e64 v45, s[0:1], 0, v29, s[0:1]
	v_and_or_b32 v68, v76, s20, v12
	v_and_or_b32 v69, v78, s20, v69
	v_lshrrev_b32_e32 v12, 16, v70
	v_lshrrev_b32_e32 v70, 16, v72
	v_add3_u32 v72, v22, v74, s11
	v_add3_u32 v74, v23, v75, s11
	v_add3_u32 v75, v20, v77, s11
	v_add3_u32 v76, v21, v79, s11
	v_bfe_u32 v77, v64, 16, 1
	v_bfe_u32 v78, v65, 16, 1
	v_bfe_u32 v79, v66, 16, 1
	v_bfe_u32 v116, v67, 16, 1
	v_pk_fma_f32 v[20:21], v[62:63], v[66:67], v[114:115]
	v_pk_fma_f32 v[22:23], v[60:61], v[64:65], v[112:113]
	v_add_co_u32_e64 v42, s[0:1], s57, v28
	s_waitcnt vmcnt(0)
; __device__ __forceinline__ unsigned pk2(float lo, float hi) { return f2bf(lo) | (f2bf(hi) << 16); }
; __device__ __forceinline__ void gla_scan(const float* UPD, const float* DEC, bf16* ST, int gtid, int gthreads) {
;     ...
; #pragma unroll
;             for (int i = 0; i < 16; ++i) {
;                 const size_t unit = (size_t)((c0 + i) * 4 + h);
;                 s = dv[i] * s + uv[i];
;                 u32x2 w; w.x = pk2(s[0], s[1]); w.y = pk2(s[2], s[3]);
;                 *(u32x2*)(ST + unit * 8192 + v * 64 + 4 * kq) = w;
;             }
	global_store_dwordx2 v[160:161], v[68:69], off sc0 sc1
	v_and_or_b32 v60, v71, s20, v12
	v_and_or_b32 v61, v73, s20, v70
	v_lshrrev_b32_e32 v12, 16, v72
	v_lshrrev_b32_e32 v62, 16, v75
	v_add3_u32 v63, v64, v77, s11
	v_add3_u32 v64, v65, v78, s11
	v_add3_u32 v65, v66, v79, s11
	v_add3_u32 v66, v67, v116, s11
	v_bfe_u32 v67, v22, 16, 1
	v_bfe_u32 v68, v23, 16, 1
	v_bfe_u32 v69, v20, 16, 1
	v_bfe_u32 v70, v21, 16, 1
	v_pk_fma_f32 v[58:59], v[58:59], v[20:21], v[110:111]
	v_pk_fma_f32 v[56:57], v[56:57], v[22:23], v[108:109]
	v_addc_co_u32_e64 v43, s[0:1], 0, v29, s[0:1]
	global_store_dwordx2 v[162:163], v[60:61], off sc0 sc1
	v_and_or_b32 v60, v74, s20, v12
	v_and_or_b32 v61, v76, s20, v62
	v_lshrrev_b32_e32 v12, 16, v63
	v_lshrrev_b32_e32 v62, 16, v65
	v_add3_u32 v63, v22, v67, s11
	v_add3_u32 v65, v23, v68, s11
	v_add3_u32 v67, v20, v69, s11
	v_add3_u32 v68, v21, v70, s11
	v_bfe_u32 v69, v56, 16, 1
	v_bfe_u32 v70, v57, 16, 1
	v_bfe_u32 v71, v58, 16, 1
	v_bfe_u32 v72, v59, 16, 1
	v_pk_fma_f32 v[20:21], v[54:55], v[58:59], v[106:107]
	v_pk_fma_f32 v[22:23], v[52:53], v[56:57], v[104:105]
	v_add_co_u32_e64 v40, s[0:1], s70, v28
	global_store_dwordx2 v[164:165], v[60:61], off sc0 sc1
	v_and_or_b32 v52, v64, s20, v12
	v_and_or_b32 v53, v66, s20, v62
	v_lshrrev_b32_e32 v12, 16, v63
	v_lshrrev_b32_e32 v54, 16, v67
	v_add3_u32 v55, v56, v69, s11
	v_add3_u32 v56, v57, v70, s11
	v_add3_u32 v57, v58, v71, s11
	v_add3_u32 v58, v59, v72, s11
	v_bfe_u32 v59, v22, 16, 1
	v_bfe_u32 v60, v23, 16, 1
	v_bfe_u32 v61, v20, 16, 1
	v_bfe_u32 v62, v21, 16, 1
	v_pk_fma_f32 v[50:51], v[50:51], v[20:21], v[102:103]
	v_pk_fma_f32 v[48:49], v[48:49], v[22:23], v[100:101]
	v_addc_co_u32_e64 v41, s[0:1], 0, v29, s[0:1]
	global_store_dwordx2 v[166:167], v[52:53], off sc0 sc1
	v_and_or_b32 v52, v65, s20, v12
	v_and_or_b32 v53, v68, s20, v54
	v_lshrrev_b32_e32 v12, 16, v55
	v_lshrrev_b32_e32 v54, 16, v57
	v_add3_u32 v55, v22, v59, s11
	v_add3_u32 v57, v23, v60, s11
	v_add3_u32 v59, v20, v61, s11
	v_add3_u32 v60, v21, v62, s11
	v_bfe_u32 v61, v48, 16, 1
	v_bfe_u32 v62, v49, 16, 1
	v_bfe_u32 v63, v50, 16, 1
	v_pk_fma_f32 v[20:21], v[98:99], v[50:51], v[158:159]
	v_pk_fma_f32 v[22:23], v[96:97], v[48:49], v[156:157]
	v_add_co_u32_e64 v38, s[0:1], s71, v28
	v_bfe_u32 v64, v51, 16, 1
	global_store_dwordx2 v[168:169], v[52:53], off sc0 sc1
	v_and_or_b32 v52, v56, s20, v12
	v_and_or_b32 v53, v58, s20, v54
	v_lshrrev_b32_e32 v12, 16, v55
	v_lshrrev_b32_e32 v54, 16, v59
	v_add3_u32 v55, v48, v61, s11
	v_add3_u32 v56, v49, v62, s11
	v_add3_u32 v50, v50, v63, s11
	v_bfe_u32 v58, v22, 16, 1
	v_bfe_u32 v59, v23, 16, 1
	v_bfe_u32 v61, v20, 16, 1
	v_bfe_u32 v62, v21, 16, 1
	v_pk_fma_f32 v[26:27], v[94:95], v[20:21], v[26:27]
	v_pk_fma_f32 v[24:25], v[92:93], v[22:23], v[24:25]
	v_addc_co_u32_e64 v39, s[0:1], 0, v29, s[0:1]
	v_add3_u32 v51, v51, v64, s11
	global_store_dwordx2 v[170:171], v[52:53], off sc0 sc1
	v_and_or_b32 v48, v57, s20, v12
	v_and_or_b32 v49, v60, s20, v54
	v_lshrrev_b32_e32 v12, 16, v55
	v_lshrrev_b32_e32 v50, 16, v50
	v_add3_u32 v52, v22, v58, s11
	v_add3_u32 v53, v23, v59, s11
	v_add3_u32 v54, v20, v61, s11
	v_add3_u32 v55, v21, v62, s11
	v_bfe_u32 v57, v24, 16, 1
	v_bfe_u32 v58, v25, 16, 1
	v_bfe_u32 v59, v26, 16, 1
	v_bfe_u32 v60, v27, 16, 1
	v_pk_fma_f32 v[20:21], v[90:91], v[26:27], v[154:155]
	v_pk_fma_f32 v[22:23], v[88:89], v[24:25], v[152:153]
	v_add_co_u32_e64 v36, s[0:1], s72, v28
	global_store_dwordx2 v[172:173], v[48:49], off sc0 sc1
	v_and_or_b32 v48, v56, s20, v12
	v_and_or_b32 v49, v51, s20, v50
	v_lshrrev_b32_e32 v12, 16, v52
	v_lshrrev_b32_e32 v50, 16, v54
	v_add3_u32 v51, v24, v57, s11
	v_add3_u32 v52, v25, v58, s11
	v_add3_u32 v54, v26, v59, s11
	v_add3_u32 v56, v27, v60, s11
	v_bfe_u32 v57, v22, 16, 1
	v_bfe_u32 v58, v23, 16, 1
	v_bfe_u32 v59, v20, 16, 1
	v_bfe_u32 v60, v21, 16, 1
	v_pk_fma_f32 v[24:25], v[86:87], v[20:21], v[150:151]
; __device__ __forceinline__ unsigned pk2(float lo, float hi) { return f2bf(lo) | (f2bf(hi) << 16); }
; __device__ __forceinline__ void gla_scan(const float* UPD, const float* DEC, bf16* ST, int gtid, int gthreads) {
;     ...
; #pragma unroll
;             for (int i = 0; i < 16; ++i) {
;                 const size_t unit = (size_t)((c0 + i) * 4 + h);
;                 s = dv[i] * s + uv[i];
;                 u32x2 w; w.x = pk2(s[0], s[1]); w.y = pk2(s[2], s[3]);
;                 *(u32x2*)(ST + unit * 8192 + v * 64 + 4 * kq) = w;
;             }
;         }
;     }
	v_pk_fma_f32 v[26:27], v[84:85], v[22:23], v[148:149]
	v_addc_co_u32_e64 v37, s[0:1], 0, v29, s[0:1]
	global_store_dwordx2 v[44:45], v[48:49], off sc0 sc1
	v_and_or_b32 v44, v53, s20, v12
	v_and_or_b32 v45, v55, s20, v50
	v_lshrrev_b32_e32 v12, 16, v51
	v_lshrrev_b32_e32 v48, 16, v54
	v_add3_u32 v49, v22, v57, s11
	v_add3_u32 v50, v23, v58, s11
	v_add3_u32 v51, v20, v59, s11
	v_add3_u32 v53, v21, v60, s11
	v_bfe_u32 v54, v26, 16, 1
	v_bfe_u32 v57, v24, 16, 1
	v_pk_fma_f32 v[20:21], v[82:83], v[24:25], v[146:147]
	v_pk_fma_f32 v[22:23], v[80:81], v[26:27], v[144:145]
	v_add_co_u32_e64 v34, s[0:1], s73, v28
	v_bfe_u32 v55, v27, 16, 1
	v_bfe_u32 v58, v25, 16, 1
	global_store_dwordx2 v[42:43], v[44:45], off sc0 sc1
	v_and_or_b32 v42, v52, s20, v12
	v_and_or_b32 v43, v56, s20, v48
	v_lshrrev_b32_e32 v12, 16, v49
	v_lshrrev_b32_e32 v44, 16, v51
	v_add3_u32 v26, v26, v54, s11
	v_add3_u32 v45, v24, v57, s11
	v_bfe_u32 v49, v22, 16, 1
	v_bfe_u32 v51, v23, 16, 1
	v_bfe_u32 v52, v20, 16, 1
	v_bfe_u32 v54, v21, 16, 1
	v_pk_fma_f32 v[10:11], v[10:11], v[20:21], v[142:143]
	v_pk_fma_f32 v[8:9], v[8:9], v[22:23], v[140:141]
	v_addc_co_u32_e64 v35, s[0:1], 0, v29, s[0:1]
	v_add3_u32 v27, v27, v55, s11
	v_add3_u32 v48, v25, v58, s11
	global_store_dwordx2 v[40:41], v[42:43], off sc0 sc1
	v_and_or_b32 v24, v50, s20, v12
	v_and_or_b32 v25, v53, s20, v44
	v_lshrrev_b32_e32 v12, 16, v26
	v_lshrrev_b32_e32 v26, 16, v45
	v_add3_u32 v22, v22, v49, s11
	v_add3_u32 v40, v23, v51, s11
	v_add3_u32 v20, v20, v52, s11
	v_add3_u32 v41, v21, v54, s11
	v_bfe_u32 v21, v8, 16, 1
	v_bfe_u32 v23, v9, 16, 1
	v_bfe_u32 v42, v10, 16, 1
	v_pk_fma_f32 v[6:7], v[6:7], v[10:11], v[138:139]
	v_pk_fma_f32 v[4:5], v[4:5], v[8:9], v[136:137]
	v_add_co_u32_e64 v32, s[0:1], s74, v28
	v_bfe_u32 v43, v11, 16, 1
	global_store_dwordx2 v[38:39], v[24:25], off sc0 sc1
	v_and_or_b32 v24, v27, s20, v12
	v_and_or_b32 v25, v48, s20, v26
	v_lshrrev_b32_e32 v12, 16, v22
	v_lshrrev_b32_e32 v26, 16, v20
	v_add3_u32 v8, v8, v21, s11
	v_add3_u32 v9, v9, v23, s11
	v_add3_u32 v10, v10, v42, s11
	v_bfe_u32 v27, v4, 16, 1
	v_bfe_u32 v39, v6, 16, 1
	v_pk_fma_f32 v[22:23], v[2:3], v[6:7], v[134:135]
	v_pk_fma_f32 v[20:21], v[0:1], v[4:5], v[132:133]
	v_addc_co_u32_e64 v33, s[0:1], 0, v29, s[0:1]
	v_add3_u32 v11, v11, v43, s11
	v_bfe_u32 v38, v5, 16, 1
	v_bfe_u32 v42, v7, 16, 1
	v_and_or_b32 v0, v40, s20, v12
	v_and_or_b32 v1, v41, s20, v26
	v_lshrrev_b32_e32 v2, 16, v8
	v_lshrrev_b32_e32 v3, 16, v10
	v_add3_u32 v4, v4, v27, s11
	v_add3_u32 v6, v6, v39, s11
	v_bfe_u32 v8, v20, 16, 1
	v_bfe_u32 v12, v22, 16, 1
	v_add_co_u32_e64 v30, s[0:1], s75, v28
	global_store_dwordx2 v[36:37], v[24:25], off sc0 sc1
	v_add3_u32 v5, v5, v38, s11
	v_add3_u32 v7, v7, v42, s11
	v_bfe_u32 v10, v21, 16, 1
	v_bfe_u32 v24, v23, 16, 1
	global_store_dwordx2 v[34:35], v[0:1], off sc0 sc1
	v_and_or_b32 v0, v9, s20, v2
	v_and_or_b32 v1, v11, s20, v3
	v_lshrrev_b32_e32 v2, 16, v4
	v_lshrrev_b32_e32 v3, 16, v6
	v_add3_u32 v4, v20, v8, s11
	v_add3_u32 v8, v22, v12, s11
	s_add_i32 s77, s77, 16
	v_addc_co_u32_e64 v31, s[0:1], 0, v29, s[0:1]
	v_add_co_u32_e32 v28, vcc, 0x1d0f0000, v28
	v_add3_u32 v6, v21, v10, s11
	v_add3_u32 v9, v23, v24, s11
	global_store_dwordx2 v[32:33], v[0:1], off sc0 sc1
	v_and_or_b32 v0, v5, s20, v2
	v_and_or_b32 v1, v7, s20, v3
	v_lshrrev_b32_e32 v2, 16, v4
	v_lshrrev_b32_e32 v3, 16, v8
	v_lshl_add_u64 v[14:15], v[14:15], 0, s[64:65]
	v_lshl_add_u64 v[16:17], v[16:17], 0, s[66:67]
	v_lshl_add_u64 v[18:19], v[18:19], 0, s[68:69]
	s_cmp_gt_u32 s77, 47
	v_addc_co_u32_e32 v29, vcc, 0, v29, vcc
	global_store_dwordx2 v[30:31], v[0:1], off sc0 sc1
	v_and_or_b32 v0, v6, s20, v2
	v_and_or_b32 v1, v9, s20, v3
	global_store_dwordx2 v[28:29], v[0:1], off sc0 sc1
	s_cbranch_scc0 .LBB0_473
	v_add_u32_e32 v46, s2, v46
	v_cmp_lt_i32_e32 vcc, s76, v46
	s_or_b64 s[62:63], vcc, s[62:63]
	v_add_u32_e32 v47, s3, v47
	s_andn2_b64 exec, exec, s[62:63]
	s_cbranch_execnz .LBB0_472

; __device__ __forceinline__ unsigned pk2(float lo, float hi) { return f2bf(lo) | (f2bf(hi) << 16); }
; __device__ __forceinline__ void gla_scan(const float* UPD, const float* DEC, bf16* ST, int gtid, int gthreads) {
;     ...
;         for (int c0 = 0; c0 < 64; c0 += 16) {
;             f32x4 dv[16], uv[16];
; #pragma unroll
;             for (int i = 0; i < 16; ++i) { const size_t unit = (size_t)((c0 + i) * 4 + h); dv[i] = *(const f32x4*)(DEC + unit * 64 + 4 * kq); uv[i] = *(const f32x4*)(UPD + unit * 8192 + v * 64 + 4 * kq); }
;             asm volatile("" : "+v"(dv[0]), "+v"(dv[1]), "+v"(dv[2]), "+v"(dv[3]), "+v"(dv[4]), "+v"(dv[5]), "+v"(dv[6]), "+v"(dv[7]) :: "memory");
;             asm volatile("" : "+v"(dv[8]), "+v"(dv[9]), "+v"(dv[10]), "+v"(dv[11]), "+v"(dv[12]), "+v"(dv[13]), "+v"(dv[14]), "+v"(dv[15]) :: "memory");
;             asm volatile("" : "+v"(uv[0]), "+v"(uv[1]), "+v"(uv[2]), "+v"(uv[3]), "+v"(uv[4]), "+v"(uv[5]), "+v"(uv[6]), "+v"(uv[7]) :: "memory");
;             asm volatile("" : "+v"(uv[8]), "+v"(uv[9]), "+v"(uv[10]), "+v"(uv[11]), "+v"(uv[12]), "+v"(uv[13]), "+v"(uv[14]), "+v"(uv[15]) :: "memory");
; #pragma unroll
;             for (int i = 0; i < 16; ++i) {
;                 const size_t unit = (size_t)((c0 + i) * 4 + h);
;                 s = dv[i] * s + uv[i];
;                 u32x2 w; w.x = pk2(s[0], s[1]); w.y = pk2(s[2], s[3]);
;                 *(u32x2*)(ST + unit * 8192 + v * 64 + 4 * kq) = w;
.LBB0_1106:
	v_lshl_add_u64 v[26:27], s[34:35], 0, v[18:19]
	v_add_co_u32_e32 v0, vcc, 0x401000, v26
	v_lshl_add_u64 v[24:25], s[34:35], 0, v[16:17]
	s_nop 0
	v_addc_co_u32_e32 v1, vcc, 0, v27, vcc
	v_add_co_u32_e32 v2, vcc, 0x400000, v26
	global_load_dwordx4 v[48:51], v[0:1], off offset:3072
	global_load_dwordx4 v[52:55], v[0:1], off offset:2048
	global_load_dwordx4 v[56:59], v[0:1], off offset:1024
	global_load_dwordx4 v[60:63], v[0:1], off
	v_addc_co_u32_e32 v3, vcc, 0, v27, vcc
	v_add_co_u32_e32 v80, vcc, 0x403000, v26
	global_load_dwordx4 v[64:67], v[2:3], off offset:3072
	global_load_dwordx4 v[68:71], v[2:3], off offset:2048
	global_load_dwordx4 v[72:75], v[2:3], off offset:1024
	global_load_dwordx4 v[76:79], v[2:3], off
	v_addc_co_u32_e32 v81, vcc, 0, v27, vcc
	v_add_co_u32_e32 v26, vcc, 0x402000, v26
	global_load_dwordx4 v[0:3], v[80:81], off offset:3072
	global_load_dwordx4 v[4:7], v[80:81], off offset:2048
	global_load_dwordx4 v[8:11], v[80:81], off offset:1024
	s_nop 0
	global_load_dwordx4 v[80:83], v[80:81], off
	v_addc_co_u32_e32 v27, vcc, 0, v27, vcc
	v_add_co_u32_e32 v100, vcc, 0x190e0000, v24
	global_load_dwordx4 v[84:87], v[26:27], off offset:3072
	global_load_dwordx4 v[88:91], v[26:27], off offset:2048
	global_load_dwordx4 v[92:95], v[26:27], off offset:1024
	global_load_dwordx4 v[96:99], v[26:27], off
	v_addc_co_u32_e32 v101, vcc, 0, v25, vcc
	v_add_co_u32_e32 v26, vcc, 0x190c0000, v24
	v_lshl_add_u64 v[28:29], s[34:35], 0, v[14:15]
	s_nop 0
	v_addc_co_u32_e32 v27, vcc, 0, v25, vcc
	v_add_co_u32_e32 v108, vcc, 0x190a0000, v24
	global_load_dwordx4 v[100:103], v[100:101], off
	s_nop 0
	global_load_dwordx4 v[104:107], v[26:27], off
	v_addc_co_u32_e32 v109, vcc, 0, v25, vcc
	v_add_co_u32_e32 v26, vcc, 0x19080000, v24
	v_add_co_u32_e64 v162, s[0:1], s29, v28
	s_nop 0
	v_addc_co_u32_e32 v27, vcc, 0, v25, vcc
	v_add_co_u32_e32 v116, vcc, 0x19060000, v24
	global_load_dwordx4 v[108:111], v[108:109], off
	s_nop 0
	global_load_dwordx4 v[112:115], v[26:27], off
	v_addc_co_u32_e32 v117, vcc, 0, v25, vcc
	v_add_co_u32_e32 v26, vcc, 0x19040000, v24
	v_addc_co_u32_e64 v163, s[0:1], 0, v29, s[0:1]
	s_nop 0
	v_addc_co_u32_e32 v27, vcc, 0, v25, vcc
	v_add_co_u32_e32 v124, vcc, 0x19020000, v24
	global_load_dwordx4 v[116:119], v[116:117], off
	s_nop 0
	global_load_dwordx4 v[120:123], v[26:27], off
	v_addc_co_u32_e32 v125, vcc, 0, v25, vcc
	v_add_co_u32_e32 v26, vcc, 0x19000000, v24
	v_add_co_u32_e64 v164, s[0:1], s30, v28
	s_nop 0
	v_addc_co_u32_e32 v27, vcc, 0, v25, vcc
	v_add_co_u32_e32 v132, vcc, 0x191e0000, v24
	global_load_dwordx4 v[124:127], v[124:125], off
	s_nop 0
	global_load_dwordx4 v[128:131], v[26:27], off
	v_addc_co_u32_e32 v133, vcc, 0, v25, vcc
	v_add_co_u32_e32 v26, vcc, 0x191c0000, v24
	v_addc_co_u32_e64 v165, s[0:1], 0, v29, s[0:1]
	s_nop 0
	v_addc_co_u32_e32 v27, vcc, 0, v25, vcc
	v_add_co_u32_e32 v140, vcc, 0x191a0000, v24
	global_load_dwordx4 v[132:135], v[132:133], off
	s_nop 0
	global_load_dwordx4 v[136:139], v[26:27], off
	v_addc_co_u32_e32 v141, vcc, 0, v25, vcc
	v_add_co_u32_e32 v26, vcc, 0x19180000, v24
	v_add_co_u32_e64 v166, s[0:1], s31, v28
	s_nop 0
	v_addc_co_u32_e32 v27, vcc, 0, v25, vcc
	v_add_co_u32_e32 v150, vcc, 0x19160000, v24
	global_load_dwordx4 v[140:143], v[140:141], off
	s_nop 0
	global_load_dwordx4 v[146:149], v[26:27], off
	v_addc_co_u32_e32 v151, vcc, 0, v25, vcc
	v_add_co_u32_e32 v26, vcc, 0x19140000, v24
	v_addc_co_u32_e64 v167, s[0:1], 0, v29, s[0:1]
	s_nop 0
	v_addc_co_u32_e32 v27, vcc, 0, v25, vcc
	v_add_co_u32_e32 v158, vcc, 0x19120000, v24
	global_load_dwordx4 v[150:153], v[150:151], off
	s_nop 0
	global_load_dwordx4 v[154:157], v[26:27], off
	v_addc_co_u32_e32 v159, vcc, 0, v25, vcc
	v_add_co_u32_e32 v160, vcc, 0x19100000, v24
	v_add_co_u32_e64 v168, s[0:1], s37, v28
	s_nop 0
	v_addc_co_u32_e32 v161, vcc, 0, v25, vcc
	global_load_dwordx4 v[24:27], v[158:159], off
	s_nop 0
	global_load_dwordx4 v[158:161], v[160:161], off
	v_addc_co_u32_e64 v169, s[0:1], 0, v29, s[0:1]
	v_add_co_u32_e64 v170, s[0:1], s39, v28
	s_waitcnt vmcnt(24)
	s_waitcnt vmcnt(16)
	s_waitcnt vmcnt(8)
	v_addc_co_u32_e64 v171, s[0:1], 0, v29, s[0:1]
	v_add_co_u32_e64 v172, s[0:1], s46, v28
	v_pk_fma_f32 v[22:23], v[22:23], v[78:79], v[130:131]
	s_nop 0
	v_addc_co_u32_e64 v173, s[0:1], 0, v29, s[0:1]
	v_pk_fma_f32 v[20:21], v[20:21], v[76:77], v[128:129]
	v_add_co_u32_e64 v174, s[0:1], s47, v28
	v_bfe_u32 v12, v20, 16, 1
	v_bfe_u32 v47, v21, 16, 1
	v_bfe_u32 v76, v22, 16, 1
	v_bfe_u32 v77, v23, 16, 1
	v_pk_fma_f32 v[74:75], v[74:75], v[22:23], v[126:127]
	v_pk_fma_f32 v[72:73], v[72:73], v[20:21], v[124:125]
	v_addc_co_u32_e64 v175, s[0:1], 0, v29, s[0:1]
	v_add3_u32 v12, v20, v12, s21
	v_add3_u32 v47, v21, v47, s21
	v_add3_u32 v76, v22, v76, s21
	v_add3_u32 v77, v23, v77, s21
	v_bfe_u32 v78, v72, 16, 1
	v_bfe_u32 v79, v73, 16, 1
	v_bfe_u32 v124, v74, 16, 1
	v_bfe_u32 v125, v75, 16, 1
	v_pk_fma_f32 v[20:21], v[70:71], v[74:75], v[122:123]
	v_pk_fma_f32 v[22:23], v[68:69], v[72:73], v[120:121]
	v_add_co_u32_e64 v44, s[0:1], s48, v28
	v_lshrrev_b32_e32 v12, 16, v12
	v_lshrrev_b32_e32 v69, 16, v76
	v_add3_u32 v70, v72, v78, s21
	v_add3_u32 v71, v73, v79, s21
	v_add3_u32 v72, v74, v124, s21
	v_add3_u32 v73, v75, v125, s21
	v_bfe_u32 v74, v22, 16, 1
	v_bfe_u32 v75, v23, 16, 1
	v_bfe_u32 v76, v20, 16, 1
	v_bfe_u32 v78, v21, 16, 1
	v_pk_fma_f32 v[66:67], v[66:67], v[20:21], v[118:119]
	v_pk_fma_f32 v[64:65], v[64:65], v[22:23], v[116:117]
	v_addc_co_u32_e64 v45, s[0:1], 0, v29, s[0:1]
	v_and_or_b32 v68, v47, s28, v12
	v_and_or_b32 v69, v77, s28, v69
	v_lshrrev_b32_e32 v12, 16, v70
	v_lshrrev_b32_e32 v47, 16, v72
	v_add3_u32 v70, v22, v74, s21
	v_add3_u32 v72, v23, v75, s21
	v_add3_u32 v74, v20, v76, s21
	v_add3_u32 v75, v21, v78, s21
	v_bfe_u32 v76, v64, 16, 1
	v_bfe_u32 v77, v65, 16, 1
	v_bfe_u32 v78, v66, 16, 1
	v_bfe_u32 v79, v67, 16, 1
	v_pk_fma_f32 v[20:21], v[62:63], v[66:67], v[114:115]
	v_pk_fma_f32 v[22:23], v[60:61], v[64:65], v[112:113]
	v_add_co_u32_e64 v42, s[0:1], s49, v28
	s_waitcnt vmcnt(0)
; __device__ __forceinline__ unsigned pk2(float lo, float hi) { return f2bf(lo) | (f2bf(hi) << 16); }
; __device__ __forceinline__ void gla_scan(const float* UPD, const float* DEC, bf16* ST, int gtid, int gthreads) {
;     ...
;             for (int i = 0; i < 16; ++i) {
;                 const size_t unit = (size_t)((c0 + i) * 4 + h);
;                 s = dv[i] * s + uv[i];
;                 u32x2 w; w.x = pk2(s[0], s[1]); w.y = pk2(s[2], s[3]);
;                 *(u32x2*)(ST + unit * 8192 + v * 64 + 4 * kq) = w;
	global_store_dwordx2 v[162:163], v[68:69], off sc0 sc1
	v_and_or_b32 v60, v71, s28, v12
	v_and_or_b32 v61, v73, s28, v47
	v_lshrrev_b32_e32 v12, 16, v70
	v_lshrrev_b32_e32 v47, 16, v74
	v_add3_u32 v62, v64, v76, s21
	v_add3_u32 v63, v65, v77, s21
	v_add3_u32 v64, v66, v78, s21
	v_add3_u32 v65, v67, v79, s21
	v_bfe_u32 v66, v22, 16, 1
	v_bfe_u32 v67, v23, 16, 1
	v_bfe_u32 v68, v20, 16, 1
	v_bfe_u32 v69, v21, 16, 1
	v_pk_fma_f32 v[58:59], v[58:59], v[20:21], v[110:111]
	v_pk_fma_f32 v[56:57], v[56:57], v[22:23], v[108:109]
	v_addc_co_u32_e64 v43, s[0:1], 0, v29, s[0:1]
	global_store_dwordx2 v[164:165], v[60:61], off sc0 sc1
	v_and_or_b32 v60, v72, s28, v12
	v_and_or_b32 v61, v75, s28, v47
	v_lshrrev_b32_e32 v12, 16, v62
	v_lshrrev_b32_e32 v47, 16, v64
	v_add3_u32 v62, v22, v66, s21
	v_add3_u32 v64, v23, v67, s21
	v_add3_u32 v66, v20, v68, s21
	v_add3_u32 v67, v21, v69, s21
	v_bfe_u32 v68, v56, 16, 1
	v_bfe_u32 v69, v57, 16, 1
	v_bfe_u32 v70, v58, 16, 1
	v_bfe_u32 v71, v59, 16, 1
	v_pk_fma_f32 v[20:21], v[54:55], v[58:59], v[106:107]
	v_pk_fma_f32 v[22:23], v[52:53], v[56:57], v[104:105]
	v_add_co_u32_e64 v40, s[0:1], s56, v28
	global_store_dwordx2 v[166:167], v[60:61], off sc0 sc1
	v_and_or_b32 v52, v63, s28, v12
	v_and_or_b32 v53, v65, s28, v47
	v_lshrrev_b32_e32 v12, 16, v62
	v_lshrrev_b32_e32 v47, 16, v66
	v_add3_u32 v54, v56, v68, s21
	v_add3_u32 v55, v57, v69, s21
	v_add3_u32 v56, v58, v70, s21
	v_add3_u32 v57, v59, v71, s21
	v_bfe_u32 v58, v22, 16, 1
	v_bfe_u32 v59, v23, 16, 1
	v_bfe_u32 v60, v20, 16, 1
	v_bfe_u32 v61, v21, 16, 1
	v_pk_fma_f32 v[50:51], v[50:51], v[20:21], v[102:103]
	v_pk_fma_f32 v[48:49], v[48:49], v[22:23], v[100:101]
	v_addc_co_u32_e64 v41, s[0:1], 0, v29, s[0:1]
	global_store_dwordx2 v[168:169], v[52:53], off sc0 sc1
	v_and_or_b32 v52, v64, s28, v12
	v_and_or_b32 v53, v67, s28, v47
	v_lshrrev_b32_e32 v12, 16, v54
	v_lshrrev_b32_e32 v47, 16, v56
	v_add3_u32 v54, v22, v58, s21
	v_add3_u32 v56, v23, v59, s21
	v_add3_u32 v58, v20, v60, s21
	v_add3_u32 v59, v21, v61, s21
	v_bfe_u32 v60, v48, 16, 1
	v_bfe_u32 v61, v49, 16, 1
	v_bfe_u32 v62, v50, 16, 1
	v_pk_fma_f32 v[20:21], v[98:99], v[50:51], v[160:161]
	v_pk_fma_f32 v[22:23], v[96:97], v[48:49], v[158:159]
	v_add_co_u32_e64 v38, s[0:1], s57, v28
	v_bfe_u32 v63, v51, 16, 1
	global_store_dwordx2 v[170:171], v[52:53], off sc0 sc1
	v_and_or_b32 v52, v55, s28, v12
	v_and_or_b32 v53, v57, s28, v47
	v_lshrrev_b32_e32 v12, 16, v54
	v_lshrrev_b32_e32 v47, 16, v58
	v_add3_u32 v54, v48, v60, s21
	v_add3_u32 v55, v49, v61, s21
	v_add3_u32 v50, v50, v62, s21
	v_bfe_u32 v57, v22, 16, 1
	v_bfe_u32 v58, v23, 16, 1
	v_bfe_u32 v60, v20, 16, 1
	v_bfe_u32 v61, v21, 16, 1
	v_pk_fma_f32 v[26:27], v[94:95], v[20:21], v[26:27]
	v_pk_fma_f32 v[24:25], v[92:93], v[22:23], v[24:25]
	v_addc_co_u32_e64 v39, s[0:1], 0, v29, s[0:1]
	v_add3_u32 v51, v51, v63, s21
	global_store_dwordx2 v[172:173], v[52:53], off sc0 sc1
	v_and_or_b32 v48, v56, s28, v12
	v_and_or_b32 v49, v59, s28, v47
	v_lshrrev_b32_e32 v12, 16, v54
	v_lshrrev_b32_e32 v47, 16, v50
	v_add3_u32 v50, v22, v57, s21
	v_add3_u32 v52, v23, v58, s21
	v_add3_u32 v53, v20, v60, s21
	v_add3_u32 v54, v21, v61, s21
	v_bfe_u32 v56, v24, 16, 1
	v_bfe_u32 v57, v25, 16, 1
	v_bfe_u32 v58, v26, 16, 1
	v_bfe_u32 v59, v27, 16, 1
	v_pk_fma_f32 v[20:21], v[90:91], v[26:27], v[156:157]
	v_pk_fma_f32 v[22:23], v[88:89], v[24:25], v[154:155]
	v_add_co_u32_e64 v36, s[0:1], s58, v28
	global_store_dwordx2 v[174:175], v[48:49], off sc0 sc1
	v_and_or_b32 v48, v55, s28, v12
	v_and_or_b32 v49, v51, s28, v47
	v_lshrrev_b32_e32 v12, 16, v50
	v_lshrrev_b32_e32 v47, 16, v53
	v_add3_u32 v50, v24, v56, s21
	v_add3_u32 v51, v25, v57, s21
	v_add3_u32 v53, v26, v58, s21
	v_add3_u32 v55, v27, v59, s21
	v_bfe_u32 v56, v22, 16, 1
	v_bfe_u32 v57, v23, 16, 1
	v_bfe_u32 v58, v20, 16, 1
	v_bfe_u32 v59, v21, 16, 1
	v_pk_fma_f32 v[24:25], v[86:87], v[20:21], v[152:153]
; __device__ __forceinline__ unsigned pk2(float lo, float hi) { return f2bf(lo) | (f2bf(hi) << 16); }
; __device__ __forceinline__ void gla_scan(const float* UPD, const float* DEC, bf16* ST, int gtid, int gthreads) {
;     for (int p = gtid; p < 4 * 128 * 16; p += gthreads) {
;         const int h = p >> 11, rem = p & 2047, v = rem >> 4, kq = rem & 15;
;         f32x4 s = (f32x4){0.f, 0.f, 0.f, 0.f};
; #pragma unroll 1
;         for (int c0 = 0; c0 < 64; c0 += 16) {
;             f32x4 dv[16], uv[16];
; #pragma unroll
;             for (int i = 0; i < 16; ++i) { const size_t unit = (size_t)((c0 + i) * 4 + h); dv[i] = *(const f32x4*)(DEC + unit * 64 + 4 * kq); uv[i] = *(const f32x4*)(UPD + unit * 8192 + v * 64 + 4 * kq); }
;             asm volatile("" : "+v"(dv[0]), "+v"(dv[1]), "+v"(dv[2]), "+v"(dv[3]), "+v"(dv[4]), "+v"(dv[5]), "+v"(dv[6]), "+v"(dv[7]) :: "memory");
;             asm volatile("" : "+v"(dv[8]), "+v"(dv[9]), "+v"(dv[10]), "+v"(dv[11]), "+v"(dv[12]), "+v"(dv[13]), "+v"(dv[14]), "+v"(dv[15]) :: "memory");
;             asm volatile("" : "+v"(uv[0]), "+v"(uv[1]), "+v"(uv[2]), "+v"(uv[3]), "+v"(uv[4]), "+v"(uv[5]), "+v"(uv[6]), "+v"(uv[7]) :: "memory");
;             asm volatile("" : "+v"(uv[8]), "+v"(uv[9]), "+v"(uv[10]), "+v"(uv[11]), "+v"(uv[12]), "+v"(uv[13]), "+v"(uv[14]), "+v"(uv[15]) :: "memory");
; #pragma unroll
;             for (int i = 0; i < 16; ++i) {
;                 const size_t unit = (size_t)((c0 + i) * 4 + h);
;                 s = dv[i] * s + uv[i];
;                 u32x2 w; w.x = pk2(s[0], s[1]); w.y = pk2(s[2], s[3]);
;                 *(u32x2*)(ST + unit * 8192 + v * 64 + 4 * kq) = w;
;             }
	v_pk_fma_f32 v[26:27], v[84:85], v[22:23], v[150:151]
	v_addc_co_u32_e64 v37, s[0:1], 0, v29, s[0:1]
	global_store_dwordx2 v[44:45], v[48:49], off sc0 sc1
	v_and_or_b32 v44, v52, s28, v12
	v_and_or_b32 v45, v54, s28, v47
	v_lshrrev_b32_e32 v12, 16, v50
	v_lshrrev_b32_e32 v47, 16, v53
	v_add3_u32 v48, v22, v56, s21
	v_add3_u32 v49, v23, v57, s21
	v_add3_u32 v50, v20, v58, s21
	v_add3_u32 v52, v21, v59, s21
	v_bfe_u32 v53, v26, 16, 1
	v_bfe_u32 v56, v24, 16, 1
	v_pk_fma_f32 v[20:21], v[82:83], v[24:25], v[148:149]
	v_pk_fma_f32 v[22:23], v[80:81], v[26:27], v[146:147]
	v_add_co_u32_e64 v34, s[0:1], s59, v28
	v_bfe_u32 v54, v27, 16, 1
	v_bfe_u32 v57, v25, 16, 1
	global_store_dwordx2 v[42:43], v[44:45], off sc0 sc1
	v_and_or_b32 v42, v51, s28, v12
	v_and_or_b32 v43, v55, s28, v47
	v_lshrrev_b32_e32 v12, 16, v48
	v_lshrrev_b32_e32 v44, 16, v50
	v_add3_u32 v26, v26, v53, s21
	v_add3_u32 v45, v24, v56, s21
	v_bfe_u32 v48, v22, 16, 1
	v_bfe_u32 v50, v23, 16, 1
	v_bfe_u32 v51, v20, 16, 1
	v_bfe_u32 v53, v21, 16, 1
	v_pk_fma_f32 v[10:11], v[10:11], v[20:21], v[142:143]
	v_pk_fma_f32 v[8:9], v[8:9], v[22:23], v[140:141]
	v_addc_co_u32_e64 v35, s[0:1], 0, v29, s[0:1]
	v_add3_u32 v27, v27, v54, s21
	v_add3_u32 v47, v25, v57, s21
	global_store_dwordx2 v[40:41], v[42:43], off sc0 sc1
	v_and_or_b32 v24, v49, s28, v12
	v_and_or_b32 v25, v52, s28, v44
	v_lshrrev_b32_e32 v12, 16, v26
	v_lshrrev_b32_e32 v26, 16, v45
	v_add3_u32 v22, v22, v48, s21
	v_add3_u32 v40, v23, v50, s21
	v_add3_u32 v20, v20, v51, s21
	v_add3_u32 v41, v21, v53, s21
	v_bfe_u32 v21, v8, 16, 1
	v_bfe_u32 v23, v9, 16, 1
	v_bfe_u32 v42, v10, 16, 1
	v_pk_fma_f32 v[6:7], v[6:7], v[10:11], v[138:139]
	v_pk_fma_f32 v[4:5], v[4:5], v[8:9], v[136:137]
	v_add_co_u32_e64 v32, s[0:1], s64, v28
	v_bfe_u32 v43, v11, 16, 1
	global_store_dwordx2 v[38:39], v[24:25], off sc0 sc1
	v_and_or_b32 v24, v27, s28, v12
	v_and_or_b32 v25, v47, s28, v26
	v_lshrrev_b32_e32 v12, 16, v22
	v_lshrrev_b32_e32 v26, 16, v20
	v_add3_u32 v8, v8, v21, s21
	v_add3_u32 v9, v9, v23, s21
	v_add3_u32 v10, v10, v42, s21
	v_bfe_u32 v27, v4, 16, 1
	v_bfe_u32 v39, v6, 16, 1
	v_pk_fma_f32 v[22:23], v[2:3], v[6:7], v[134:135]
	v_pk_fma_f32 v[20:21], v[0:1], v[4:5], v[132:133]
	v_addc_co_u32_e64 v33, s[0:1], 0, v29, s[0:1]
	v_add3_u32 v11, v11, v43, s21
	v_bfe_u32 v38, v5, 16, 1
	v_bfe_u32 v42, v7, 16, 1
	v_and_or_b32 v0, v40, s28, v12
	v_and_or_b32 v1, v41, s28, v26
	v_lshrrev_b32_e32 v2, 16, v8
	v_lshrrev_b32_e32 v3, 16, v10
	v_add3_u32 v4, v4, v27, s21
	v_add3_u32 v6, v6, v39, s21
	v_bfe_u32 v8, v20, 16, 1
	v_bfe_u32 v12, v22, 16, 1
	v_add_co_u32_e64 v30, s[0:1], s65, v28
	global_store_dwordx2 v[36:37], v[24:25], off sc0 sc1
	v_add3_u32 v5, v5, v38, s21
	v_add3_u32 v7, v7, v42, s21
	v_bfe_u32 v10, v21, 16, 1
	v_bfe_u32 v24, v23, 16, 1
	global_store_dwordx2 v[34:35], v[0:1], off sc0 sc1
	v_and_or_b32 v0, v9, s28, v2
	v_and_or_b32 v1, v11, s28, v3
	v_lshrrev_b32_e32 v2, 16, v4
	v_lshrrev_b32_e32 v3, 16, v6
	v_add3_u32 v4, v20, v8, s21
	v_add3_u32 v8, v22, v12, s21
	s_add_i32 s67, s67, 16
	v_addc_co_u32_e64 v31, s[0:1], 0, v29, s[0:1]
	v_add_co_u32_e32 v28, vcc, 0x1d0f0000, v28
	v_add3_u32 v6, v21, v10, s21
	v_add3_u32 v9, v23, v24, s21
	global_store_dwordx2 v[32:33], v[0:1], off sc0 sc1
	v_and_or_b32 v0, v5, s28, v2
	v_and_or_b32 v1, v7, s28, v3
	v_lshrrev_b32_e32 v2, 16, v4
	v_lshrrev_b32_e32 v3, 16, v8
	v_lshl_add_u64 v[14:15], v[14:15], 0, s[12:13]
	v_lshl_add_u64 v[16:17], v[16:17], 0, s[14:15]
	v_lshl_add_u64 v[18:19], v[18:19], 0, s[16:17]
	s_cmp_gt_u32 s67, 47
	v_addc_co_u32_e32 v29, vcc, 0, v29, vcc
	global_store_dwordx2 v[30:31], v[0:1], off sc0 sc1
	v_and_or_b32 v0, v6, s28, v2
	v_and_or_b32 v1, v9, s28, v3
	global_store_dwordx2 v[28:29], v[0:1], off sc0 sc1
	s_cbranch_scc0 .LBB0_1106
	v_add_u32_e32 v203, s11, v203
	v_cmp_lt_i32_e32 vcc, s66, v203
	s_or_b64 s[6:7], vcc, s[6:7]
	v_add_u32_e32 v46, s20, v46
	s_andn2_b64 exec, exec, s[6:7]
	s_cbranch_execnz .LBB0_1105
